# static s_setprio 1 for waves 4-7 for the whole kernel (also SB / HGRN MFMA loops), flips deleted
# baseline (speedup 1.0000x reference)
; #define LAS __attribute__((address_space(3)))
; DI unsigned xb_add(unsigned* p, unsigned v) { return __hip_atomic_fetch_add(p, v, __ATOMIC_RELAXED, __HIP_MEMORY_SCOPE_AGENT); }
; DI unsigned xb_xcc_id() { return (unsigned)__builtin_amdgcn_s_getreg((3 << 11) | 20) & 0xFu; }
; DI XcdBarrier xcd_barrier_post(unsigned* bar, volatile LAS unsigned* st) {
;     XcdBarrier b; b.bar = bar; b.x = xb_xcc_id(); b.st = st;
;     if (threadIdx.x == 0) (void)xb_add(&bar[XB_XCNT(b.x)], 1u);
;     return b;
; __global__ void __launch_bounds__(NTH, 2) fwd_megakernel(Params P0) {
;     extern __shared__ __attribute__((aligned(16))) unsigned char lds_raw[];
;     LAS unsigned char* lds = (LAS unsigned char*)lds_raw;
;     cg::grid_group grid = cg::this_grid();
;     if (threadIdx.x < 4) ((LAS unsigned*)(lds + LDS_BARST))[threadIdx.x] = 0u;
;     __syncthreads();
;     const XcdBarrier xbar = xcd_barrier_post((unsigned*)P0.ws, (volatile LAS unsigned*)(lds + LDS_BARST));
_Z14fwd_megakernel6Params:
	s_load_dwordx2 s[80:81], s[0:1], 0x90
	s_add_u32 s6, s0, 0xa0
	v_and_b32_e32 v228, 0x3ff, v0
	s_mov_b32 s28, s2
	s_addc_u32 s7, s1, 0
	v_cmp_gt_u32_e32 vcc, 4, v228
	s_and_saveexec_b64 s[2:3], vcc
	v_lshl_add_u32 v1, v228, 2, 0
	v_add_u32_e32 v1, 0x23ff0, v1
	v_mov_b32_e32 v2, 0
	ds_write_b32 v1, v2
	s_or_b64 exec, exec, s[2:3]
	s_load_dwordx2 s[54:55], s[0:1], 0xa0
	s_load_dword s79, s[0:1], 0x98
	v_cmp_eq_u32_e64 s[4:5], 0, v228
	s_waitcnt lgkmcnt(0)
	s_barrier
	v_readfirstlane_b32 s2, v228
	s_nop 3
	s_lshr_b32 s2, s2, 6
	s_cmp_ge_u32 s2, 4
	s_cbranch_scc0 .Lprio_done
	s_setprio 1
.Lprio_done:
	s_getreg_b32 s2, hwreg(HW_REG_XCC_ID, 0, 4)
	v_writelane_b32 v253, s4, 0
	s_and_b32 s14, s2, 15
	s_nop 0
	v_writelane_b32 v253, s5, 1
	s_and_saveexec_b64 s[2:3], s[4:5]
	s_cbranch_execz .LBB0_5
	s_mov_b64 s[8:9], exec
	v_mbcnt_lo_u32_b32 v1, s8, 0
	v_mbcnt_hi_u32_b32 v1, s9, v1
	v_cmp_eq_u32_e32 vcc, 0, v1
	s_and_b64 s[12:13], exec, vcc
	s_mov_b64 exec, s[12:13]
	s_cbranch_execz .LBB0_5
	s_lshl_b32 s12, s14, 8
	s_bcnt1_i32_b64 s8, s[8:9]
	v_mov_b32_e32 v1, s12
	v_mov_b32_e32 v2, s8
	global_atomic_add v1, v2, s[80:81] offset:1024
